# mix-in epilogue rope path: cos/sin rows prefetched one row group ahead instead of a drained load per group
# speedup vs baseline: 1.0071x; 1.0050x over previous
.LBB0_246:
	s_add_i32 s34, s64, -6
	s_cmp_gt_u32 s34, 3
	s_cselect_b64 s[34:35], -1, 0
	s_cmp_lt_i32 s64, 5
	v_lshl_add_u32 v194, s62, 8, v3
	s_cselect_b64 s[44:45], -1, 0
	s_cmp_lg_u32 s64, 4
	v_and_b32_e32 v132, 0x7cf, v194
	v_add_u32_e32 v190, 0x80, v194
	v_add_u32_e32 v186, 0x90, v194
	v_add_u32_e32 v182, 0xa0, v194
	v_add_u32_e32 v178, 0xb0, v194
	s_cselect_b64 s[62:63], -1, 0
	s_lshl_b32 s36, s64, 8
	v_lshl_add_u32 v132, v132, 2, s92
	v_bitop3_b32 v133, v194, s5, 16 bitop3:0xc8
	v_bitop3_b32 v134, v194, s8, 32 bitop3:0xc8
	v_bitop3_b32 v135, v194, s9, 48 bitop3:0xc8
	v_and_b32_e32 v136, 0x7cf, v190
	v_and_b32_e32 v137, 0x7df, v186
	v_and_b32_e32 v138, 0x7ef, v182
	v_and_b32_e32 v139, 0x7ff, v178
	s_add_i32 s37, s36, 0xfffffe00
	v_lshl_add_u32 v133, v133, 2, s92
	v_lshl_add_u32 v134, v134, 2, s92
	v_lshl_add_u32 v135, v135, 2, s92
	v_lshl_add_u32 v136, v136, 2, s92
	v_lshl_add_u32 v137, v137, 2, s92
	v_lshl_add_u32 v138, v138, 2, s92
	v_lshl_add_u32 v139, v139, 2, s92
	ds_read_b32 v132, v132
	ds_read_b32 v200, v133
	ds_read_b32 v198, v134
	ds_read_b32 v196, v135
	ds_read_b32 v192, v136
	ds_read_b32 v188, v137
	ds_read_b32 v184, v138
	ds_read_b32 v180, v139
	s_cmp_lt_i32 s64, 6
	s_cselect_b32 s36, s36, s37
	s_waitcnt lgkmcnt(0)
	v_pk_mul_f32 v[130:131], v[130:131], v[132:133] op_sel_hi:[1,0]
	v_pk_mul_f32 v[128:129], v[128:129], v[132:133] op_sel_hi:[1,0]
	v_pk_mul_f32 v[126:127], v[126:127], v[132:133] op_sel_hi:[1,0]
	v_pk_mul_f32 v[124:125], v[124:125], v[132:133] op_sel_hi:[1,0]
	v_pk_mul_f32 v[122:123], v[122:123], v[132:133] op_sel_hi:[1,0]
	v_pk_mul_f32 v[120:121], v[120:121], v[132:133] op_sel_hi:[1,0]
	v_pk_mul_f32 v[118:119], v[118:119], v[132:133] op_sel_hi:[1,0]
	v_pk_mul_f32 v[116:117], v[116:117], v[132:133] op_sel_hi:[1,0]
	v_mov_b64_e32 v[132:133], s[22:23]
	v_or_b32_e32 v176, s36, v154
	v_mad_i64_i32 v[202:203], s[36:37], v194, s89, v[132:133]
	v_cndmask_b32_e64 v132, 0, 1, s[44:45]
	v_ashrrev_i32_e32 v177, 31, v176
	s_mov_b64 s[36:37], -1
	s_and_b64 vcc, exec, s[34:35]
	v_cmp_ne_u32_e64 s[44:45], 1, v132
	s_cbranch_vccz .LBB0_256
	s_and_b64 vcc, exec, s[44:45]
	s_cbranch_vccnz .LBB0_252
	s_andn2_b64 vcc, exec, s[50:51]
	s_cbranch_vccnz .LBB0_253
	v_and_b32_e32 v133, 64, v221
	v_xor_b32_e32 v132, 16, v221
	v_add_u32_e32 v133, 64, v133
	v_cmp_lt_i32_e32 vcc, v132, v133
	v_mov_b64_e32 v[146:147], v[130:131]
	v_mov_b64_e32 v[138:139], v[122:123]
	v_cndmask_b32_e32 v132, v221, v132, vcc
	v_lshlrev_b32_e32 v132, 2, v132
	ds_bpermute_b32 v216, v132, v128
	ds_bpermute_b32 v212, v132, v124
	ds_bpermute_b32 v208, v132, v120
	ds_bpermute_b32 v204, v132, v116
	ds_bpermute_b32 v217, v132, v129
	ds_bpermute_b32 v213, v132, v125
	ds_bpermute_b32 v209, v132, v121
	ds_bpermute_b32 v205, v132, v117
	ds_bpermute_b32 v218, v132, v130
	ds_bpermute_b32 v214, v132, v126
	ds_bpermute_b32 v210, v132, v122
	ds_bpermute_b32 v206, v132, v118
	ds_bpermute_b32 v219, v132, v131
	ds_bpermute_b32 v215, v132, v127
	ds_bpermute_b32 v211, v132, v123
	ds_bpermute_b32 v207, v132, v119
	v_mov_b64_e32 v[134:135], v[118:119]
	v_mov_b64_e32 v[142:143], v[126:127]
	v_mov_b64_e32 v[144:145], v[128:129]
	v_mov_b64_e32 v[132:133], v[116:117]
	v_mov_b64_e32 v[136:137], v[120:121]
	v_mov_b64_e32 v[140:141], v[124:125]
	s_and_saveexec_b64 s[46:47], s[38:39]
	s_cbranch_execz .LBB0_251
	v_ashrrev_i32_e32 v195, 31, v194
	v_lshlrev_b64 v[132:133], 6, v[194:195]
	v_lshl_add_u64 v[140:141], s[26:27], 0, v[132:133]
	global_load_dwordx4 v[132:135], v[140:141], off offset:32
	global_load_dwordx4 v[136:139], v[140:141], off offset:48
	global_load_dwordx4 v[228:231], v[140:141], off
	global_load_dwordx4 v[232:235], v[140:141], off offset:16
	s_waitcnt vmcnt(0)
	v_mov_b32_e32 v254, v140
	v_mov_b32_e32 v255, v141
	v_add_co_u32_e32 v254, vcc, 0x400, v254
	s_nop 1
	v_addc_co_u32_e32 v255, vcc, 0, v255, vcc
	global_load_dwordx4 v[236:239], v[254:255], off offset:32
	global_load_dwordx4 v[242:245], v[254:255], off offset:48
	global_load_dwordx4 v[246:249], v[254:255], off
	global_load_dwordx4 v[250:253], v[254:255], off offset:16
	v_xor_b32_e32 v140, 0x80000000, v132
	v_xor_b32_e32 v141, 0x80000000, v133
	v_xor_b32_e32 v142, 0x80000000, v134
	v_xor_b32_e32 v143, 0x80000000, v135
	v_xor_b32_e32 v144, 0x80000000, v136
	v_xor_b32_e32 v145, 0x80000000, v137
	v_xor_b32_e32 v146, 0x80000000, v138
	v_xor_b32_e32 v147, 0x80000000, v139
	v_cndmask_b32_e64 v135, v135, v143, s[40:41]
	v_cndmask_b32_e64 v134, v134, v142, s[40:41]
	v_cndmask_b32_e64 v133, v133, v141, s[40:41]
	v_cndmask_b32_e64 v132, v132, v140, s[40:41]
	v_cndmask_b32_e64 v139, v139, v147, s[40:41]
	v_cndmask_b32_e64 v138, v138, v146, s[40:41]
	v_cndmask_b32_e64 v137, v137, v145, s[40:41]
	v_cndmask_b32_e64 v136, v136, v144, s[40:41]
	s_waitcnt lgkmcnt(11)
	v_pk_mul_f32 v[140:141], v[132:133], v[216:217]
	s_waitcnt lgkmcnt(3)
	v_pk_mul_f32 v[142:143], v[134:135], v[218:219]
	v_pk_mul_f32 v[212:213], v[136:137], v[212:213]
	s_waitcnt lgkmcnt(2)
	v_pk_mul_f32 v[214:215], v[138:139], v[214:215]
	v_pk_mul_f32 v[132:133], v[132:133], v[208:209]
	s_waitcnt lgkmcnt(1)
	v_pk_mul_f32 v[134:135], v[134:135], v[210:211]
	v_pk_mul_f32 v[204:205], v[136:137], v[204:205]
	s_waitcnt lgkmcnt(0)
	v_pk_mul_f32 v[206:207], v[138:139], v[206:207]
	v_pk_fma_f32 v[146:147], v[130:131], v[230:231], v[142:143]
	v_pk_fma_f32 v[144:145], v[128:129], v[228:229], v[140:141]
	v_pk_fma_f32 v[142:143], v[126:127], v[234:235], v[214:215]
	v_pk_fma_f32 v[140:141], v[124:125], v[232:233], v[212:213]
	v_pk_fma_f32 v[138:139], v[122:123], v[230:231], v[134:135]
	v_pk_fma_f32 v[136:137], v[120:121], v[228:229], v[132:133]
	v_pk_fma_f32 v[134:135], v[118:119], v[234:235], v[206:207]
	v_pk_fma_f32 v[132:133], v[116:117], v[232:233], v[204:205]

.LBB0_258:
	v_or_b32_e32 v144, 16, v194
	s_nop 0
	v_mov_b64_e32 v[116:117], s[22:23]
	v_mad_i64_i32 v[134:135], s[36:37], v144, s89, v[116:117]
	v_cndmask_b32_e64 v116, 0, 1, s[34:35]
	v_pk_mul_f32 v[114:115], v[114:115], v[200:201] op_sel_hi:[1,0]
	v_pk_mul_f32 v[112:113], v[112:113], v[200:201] op_sel_hi:[1,0]
	v_pk_mul_f32 v[110:111], v[110:111], v[200:201] op_sel_hi:[1,0]
	v_pk_mul_f32 v[108:109], v[108:109], v[200:201] op_sel_hi:[1,0]
	v_pk_mul_f32 v[106:107], v[106:107], v[200:201] op_sel_hi:[1,0]
	v_pk_mul_f32 v[104:105], v[104:105], v[200:201] op_sel_hi:[1,0]
	v_pk_mul_f32 v[102:103], v[102:103], v[200:201] op_sel_hi:[1,0]
	v_pk_mul_f32 v[100:101], v[100:101], v[200:201] op_sel_hi:[1,0]
	v_cmp_ne_u32_e64 s[46:47], 1, v116
	s_andn2_b64 vcc, exec, s[34:35]
	s_mov_b64 s[34:35], -1
	s_cbranch_vccnz .LBB0_268
	s_and_b64 vcc, exec, s[44:45]
	s_cbranch_vccnz .LBB0_264
	s_andn2_b64 vcc, exec, s[50:51]
	s_cbranch_vccnz .LBB0_265
	v_and_b32_e32 v117, 64, v221
	v_xor_b32_e32 v116, 16, v221
	v_add_u32_e32 v117, 64, v117
	v_cmp_lt_i32_e32 vcc, v116, v117
	v_mov_b64_e32 v[130:131], v[114:115]
	v_mov_b64_e32 v[122:123], v[106:107]
	v_cndmask_b32_e32 v116, v221, v116, vcc
	v_lshlrev_b32_e32 v116, 2, v116
	ds_bpermute_b32 v202, v116, v112
	ds_bpermute_b32 v146, v116, v108
	ds_bpermute_b32 v140, v116, v104
	ds_bpermute_b32 v136, v116, v100
	ds_bpermute_b32 v203, v116, v113
	ds_bpermute_b32 v147, v116, v109
	ds_bpermute_b32 v141, v116, v105
	ds_bpermute_b32 v137, v116, v101
	s_waitcnt lgkmcnt(0)
	ds_bpermute_b32 v204, v116, v114
	ds_bpermute_b32 v200, v116, v110
	ds_bpermute_b32 v142, v116, v106
	ds_bpermute_b32 v138, v116, v102
	ds_bpermute_b32 v205, v116, v115
	ds_bpermute_b32 v201, v116, v111
	ds_bpermute_b32 v143, v116, v107
	ds_bpermute_b32 v139, v116, v103
	v_mov_b64_e32 v[118:119], v[102:103]
	v_mov_b64_e32 v[126:127], v[110:111]
	v_mov_b64_e32 v[128:129], v[112:113]
	v_mov_b64_e32 v[116:117], v[100:101]
	v_mov_b64_e32 v[120:121], v[104:105]
	v_mov_b64_e32 v[124:125], v[108:109]
	s_and_saveexec_b64 s[34:35], s[38:39]
	s_cbranch_execz .LBB0_263
	v_ashrrev_i32_e32 v145, 31, v144
	v_lshlrev_b64 v[116:117], 6, v[144:145]
	v_lshl_add_u64 v[124:125], s[26:27], 0, v[116:117]
	s_waitcnt vmcnt(2)
	v_mov_b32_e32 v116, v236
	v_mov_b32_e32 v117, v237
	v_mov_b32_e32 v118, v238
	v_mov_b32_e32 v119, v239
	v_mov_b32_e32 v120, v242
	v_mov_b32_e32 v121, v243
	v_mov_b32_e32 v122, v244
	v_mov_b32_e32 v123, v245
	v_mov_b32_e32 v206, v246
	v_mov_b32_e32 v207, v247
	v_mov_b32_e32 v208, v248
	v_mov_b32_e32 v209, v249
	v_mov_b32_e32 v210, v250
	v_mov_b32_e32 v211, v251
	v_mov_b32_e32 v212, v252
	v_mov_b32_e32 v213, v253
	v_add_co_u32_e32 v254, vcc, 0x400, v254
	s_nop 1
	v_addc_co_u32_e32 v255, vcc, 0, v255, vcc
	global_load_dwordx4 v[236:239], v[254:255], off offset:32
	global_load_dwordx4 v[242:245], v[254:255], off offset:48
	global_load_dwordx4 v[246:249], v[254:255], off
	global_load_dwordx4 v[250:253], v[254:255], off offset:16
	v_xor_b32_e32 v124, 0x80000000, v116
	v_xor_b32_e32 v125, 0x80000000, v117
	v_xor_b32_e32 v126, 0x80000000, v118
	v_xor_b32_e32 v127, 0x80000000, v119
	v_xor_b32_e32 v128, 0x80000000, v120
	v_xor_b32_e32 v129, 0x80000000, v121
	v_xor_b32_e32 v130, 0x80000000, v122
	v_xor_b32_e32 v131, 0x80000000, v123
	v_cndmask_b32_e64 v119, v119, v127, s[40:41]
	v_cndmask_b32_e64 v118, v118, v126, s[40:41]
	v_cndmask_b32_e64 v117, v117, v125, s[40:41]
	v_cndmask_b32_e64 v116, v116, v124, s[40:41]
	v_cndmask_b32_e64 v123, v123, v131, s[40:41]
	v_cndmask_b32_e64 v122, v122, v130, s[40:41]
	v_cndmask_b32_e64 v121, v121, v129, s[40:41]
	v_cndmask_b32_e64 v120, v120, v128, s[40:41]
	v_pk_mul_f32 v[124:125], v[116:117], v[202:203]
	s_waitcnt lgkmcnt(3)
	v_pk_mul_f32 v[126:127], v[118:119], v[204:205]
	v_pk_mul_f32 v[144:145], v[120:121], v[146:147]
	s_waitcnt lgkmcnt(2)
	v_pk_mul_f32 v[146:147], v[122:123], v[200:201]
	v_pk_mul_f32 v[116:117], v[116:117], v[140:141]
	s_waitcnt lgkmcnt(1)
	v_pk_mul_f32 v[118:119], v[118:119], v[142:143]
	v_pk_mul_f32 v[136:137], v[120:121], v[136:137]
	s_waitcnt lgkmcnt(0)
	v_pk_mul_f32 v[138:139], v[122:123], v[138:139]
	v_pk_fma_f32 v[130:131], v[114:115], v[208:209], v[126:127]
	v_pk_fma_f32 v[128:129], v[112:113], v[206:207], v[124:125]
	v_pk_fma_f32 v[126:127], v[110:111], v[212:213], v[146:147]
	v_pk_fma_f32 v[124:125], v[108:109], v[210:211], v[144:145]
	v_pk_fma_f32 v[122:123], v[106:107], v[208:209], v[118:119]
	v_pk_fma_f32 v[120:121], v[104:105], v[206:207], v[116:117]
	v_pk_fma_f32 v[118:119], v[102:103], v[212:213], v[138:139]
	v_pk_fma_f32 v[116:117], v[100:101], v[210:211], v[136:137]

.LBB0_270:
	v_or_b32_e32 v126, 32, v194
	s_nop 0
	v_mov_b64_e32 v[100:101], s[22:23]
	v_mad_i64_i32 v[116:117], s[34:35], v126, s89, v[100:101]
	v_pk_mul_f32 v[98:99], v[98:99], v[198:199] op_sel_hi:[1,0]
	v_pk_mul_f32 v[96:97], v[96:97], v[198:199] op_sel_hi:[1,0]
	v_pk_mul_f32 v[94:95], v[94:95], v[198:199] op_sel_hi:[1,0]
	v_pk_mul_f32 v[92:93], v[92:93], v[198:199] op_sel_hi:[1,0]
	v_pk_mul_f32 v[90:91], v[90:91], v[198:199] op_sel_hi:[1,0]
	v_pk_mul_f32 v[88:89], v[88:89], v[198:199] op_sel_hi:[1,0]
	v_pk_mul_f32 v[86:87], v[86:87], v[198:199] op_sel_hi:[1,0]
	v_pk_mul_f32 v[84:85], v[84:85], v[198:199] op_sel_hi:[1,0]
	s_and_b64 vcc, exec, s[46:47]
	s_mov_b64 s[34:35], -1
	s_cbranch_vccnz .LBB0_280
	s_and_b64 vcc, exec, s[44:45]
	s_cbranch_vccnz .LBB0_276
	s_andn2_b64 vcc, exec, s[50:51]
	s_cbranch_vccnz .LBB0_277
	v_and_b32_e32 v101, 64, v221
	v_xor_b32_e32 v100, 16, v221
	v_add_u32_e32 v101, 64, v101
	v_cmp_lt_i32_e32 vcc, v100, v101
	v_mov_b64_e32 v[114:115], v[98:99]
	v_mov_b64_e32 v[106:107], v[90:91]
	v_cndmask_b32_e32 v100, v221, v100, vcc
	v_lshlrev_b32_e32 v100, 2, v100
	ds_bpermute_b32 v134, v100, v96
	ds_bpermute_b32 v128, v100, v92
	ds_bpermute_b32 v122, v100, v88
	ds_bpermute_b32 v118, v100, v84
	ds_bpermute_b32 v135, v100, v97
	ds_bpermute_b32 v129, v100, v93
	ds_bpermute_b32 v123, v100, v89
	ds_bpermute_b32 v119, v100, v85
	ds_bpermute_b32 v136, v100, v98
	ds_bpermute_b32 v130, v100, v94
	ds_bpermute_b32 v124, v100, v90
	ds_bpermute_b32 v120, v100, v86
	ds_bpermute_b32 v137, v100, v99
	ds_bpermute_b32 v131, v100, v95
	ds_bpermute_b32 v125, v100, v91
	ds_bpermute_b32 v121, v100, v87
	v_mov_b64_e32 v[102:103], v[86:87]
	v_mov_b64_e32 v[110:111], v[94:95]
	v_mov_b64_e32 v[112:113], v[96:97]
	v_mov_b64_e32 v[100:101], v[84:85]
	v_mov_b64_e32 v[104:105], v[88:89]
	v_mov_b64_e32 v[108:109], v[92:93]
	s_and_saveexec_b64 s[34:35], s[38:39]
	s_cbranch_execz .LBB0_275
	v_ashrrev_i32_e32 v127, 31, v126
	v_lshlrev_b64 v[100:101], 6, v[126:127]
	v_lshl_add_u64 v[108:109], s[26:27], 0, v[100:101]
	s_waitcnt lgkmcnt(0)
	s_waitcnt vmcnt(2)
	v_mov_b32_e32 v100, v236
	v_mov_b32_e32 v101, v237
	v_mov_b32_e32 v102, v238
	v_mov_b32_e32 v103, v239
	v_mov_b32_e32 v104, v242
	v_mov_b32_e32 v105, v243
	v_mov_b32_e32 v106, v244
	v_mov_b32_e32 v107, v245
	v_mov_b32_e32 v138, v246
	v_mov_b32_e32 v139, v247
	v_mov_b32_e32 v140, v248
	v_mov_b32_e32 v141, v249
	v_mov_b32_e32 v142, v250
	v_mov_b32_e32 v143, v251
	v_mov_b32_e32 v144, v252
	v_mov_b32_e32 v145, v253
	v_add_co_u32_e32 v254, vcc, 0x400, v254
	s_nop 1
	v_addc_co_u32_e32 v255, vcc, 0, v255, vcc
	global_load_dwordx4 v[236:239], v[254:255], off offset:32
	global_load_dwordx4 v[242:245], v[254:255], off offset:48
	global_load_dwordx4 v[246:249], v[254:255], off
	global_load_dwordx4 v[250:253], v[254:255], off offset:16
	v_xor_b32_e32 v108, 0x80000000, v100
	v_xor_b32_e32 v109, 0x80000000, v101
	v_xor_b32_e32 v110, 0x80000000, v102
	v_xor_b32_e32 v111, 0x80000000, v103
	v_xor_b32_e32 v112, 0x80000000, v104
	v_xor_b32_e32 v113, 0x80000000, v105
	v_xor_b32_e32 v114, 0x80000000, v106
	v_xor_b32_e32 v115, 0x80000000, v107
	v_cndmask_b32_e64 v103, v103, v111, s[40:41]
	v_cndmask_b32_e64 v102, v102, v110, s[40:41]
	v_cndmask_b32_e64 v101, v101, v109, s[40:41]
	v_cndmask_b32_e64 v100, v100, v108, s[40:41]
	v_cndmask_b32_e64 v107, v107, v115, s[40:41]
	v_cndmask_b32_e64 v106, v106, v114, s[40:41]
	v_cndmask_b32_e64 v105, v105, v113, s[40:41]
	v_cndmask_b32_e64 v104, v104, v112, s[40:41]
	v_pk_mul_f32 v[108:109], v[100:101], v[134:135]
	v_pk_mul_f32 v[110:111], v[102:103], v[136:137]
	v_pk_mul_f32 v[126:127], v[104:105], v[128:129]
	v_pk_mul_f32 v[128:129], v[106:107], v[130:131]
	v_pk_mul_f32 v[100:101], v[100:101], v[122:123]
	v_pk_mul_f32 v[102:103], v[102:103], v[124:125]
	v_pk_mul_f32 v[118:119], v[104:105], v[118:119]
	v_pk_mul_f32 v[120:121], v[106:107], v[120:121]
	v_pk_fma_f32 v[114:115], v[98:99], v[140:141], v[110:111]
	v_pk_fma_f32 v[112:113], v[96:97], v[138:139], v[108:109]
	v_pk_fma_f32 v[110:111], v[94:95], v[144:145], v[128:129]
	v_pk_fma_f32 v[108:109], v[92:93], v[142:143], v[126:127]
	v_pk_fma_f32 v[106:107], v[90:91], v[140:141], v[102:103]
	v_pk_fma_f32 v[104:105], v[88:89], v[138:139], v[100:101]
	v_pk_fma_f32 v[102:103], v[86:87], v[144:145], v[120:121]
	v_pk_fma_f32 v[100:101], v[84:85], v[142:143], v[118:119]

.LBB0_282:
	v_or_b32_e32 v110, 48, v194
	s_nop 0
	v_mov_b64_e32 v[84:85], s[22:23]
	v_mad_i64_i32 v[100:101], s[34:35], v110, s89, v[84:85]
	v_pk_mul_f32 v[82:83], v[82:83], v[196:197] op_sel_hi:[1,0]
	v_pk_mul_f32 v[80:81], v[80:81], v[196:197] op_sel_hi:[1,0]
	v_pk_mul_f32 v[78:79], v[78:79], v[196:197] op_sel_hi:[1,0]
	v_pk_mul_f32 v[76:77], v[76:77], v[196:197] op_sel_hi:[1,0]
	v_pk_mul_f32 v[74:75], v[74:75], v[196:197] op_sel_hi:[1,0]
	v_pk_mul_f32 v[72:73], v[72:73], v[196:197] op_sel_hi:[1,0]
	v_pk_mul_f32 v[70:71], v[70:71], v[196:197] op_sel_hi:[1,0]
	v_pk_mul_f32 v[68:69], v[68:69], v[196:197] op_sel_hi:[1,0]
	s_and_b64 vcc, exec, s[46:47]
	s_mov_b64 s[34:35], -1
	s_cbranch_vccnz .LBB0_292
	s_and_b64 vcc, exec, s[44:45]
	s_cbranch_vccnz .LBB0_288
	s_andn2_b64 vcc, exec, s[50:51]
	s_cbranch_vccnz .LBB0_289
	v_and_b32_e32 v85, 64, v221
	v_xor_b32_e32 v84, 16, v221
	v_add_u32_e32 v85, 64, v85
	v_cmp_lt_i32_e32 vcc, v84, v85
	v_mov_b64_e32 v[98:99], v[82:83]
	v_mov_b64_e32 v[90:91], v[74:75]
	v_cndmask_b32_e32 v84, v221, v84, vcc
	v_lshlrev_b32_e32 v84, 2, v84
	ds_bpermute_b32 v116, v84, v80
	ds_bpermute_b32 v112, v84, v76
	ds_bpermute_b32 v106, v84, v72
	ds_bpermute_b32 v102, v84, v68
	ds_bpermute_b32 v117, v84, v81
	ds_bpermute_b32 v113, v84, v77
	ds_bpermute_b32 v107, v84, v73
	ds_bpermute_b32 v103, v84, v69
	s_waitcnt lgkmcnt(0)
	ds_bpermute_b32 v118, v84, v82
	ds_bpermute_b32 v114, v84, v78
	ds_bpermute_b32 v108, v84, v74
	ds_bpermute_b32 v104, v84, v70
	ds_bpermute_b32 v119, v84, v83
	ds_bpermute_b32 v115, v84, v79
	ds_bpermute_b32 v109, v84, v75
	ds_bpermute_b32 v105, v84, v71
	v_mov_b64_e32 v[86:87], v[70:71]
	v_mov_b64_e32 v[94:95], v[78:79]
	v_mov_b64_e32 v[96:97], v[80:81]
	v_mov_b64_e32 v[84:85], v[68:69]
	v_mov_b64_e32 v[88:89], v[72:73]
	v_mov_b64_e32 v[92:93], v[76:77]
	s_and_saveexec_b64 s[34:35], s[38:39]
	s_cbranch_execz .LBB0_287
	v_ashrrev_i32_e32 v111, 31, v110
	v_lshlrev_b64 v[84:85], 6, v[110:111]
	v_lshl_add_u64 v[92:93], s[26:27], 0, v[84:85]
	s_waitcnt vmcnt(2)
	v_mov_b32_e32 v84, v236
	v_mov_b32_e32 v85, v237
	v_mov_b32_e32 v86, v238
	v_mov_b32_e32 v87, v239
	v_mov_b32_e32 v88, v242
	v_mov_b32_e32 v89, v243
	v_mov_b32_e32 v90, v244
	v_mov_b32_e32 v91, v245
	v_mov_b32_e32 v120, v246
	v_mov_b32_e32 v121, v247
	v_mov_b32_e32 v122, v248
	v_mov_b32_e32 v123, v249
	v_mov_b32_e32 v124, v250
	v_mov_b32_e32 v125, v251
	v_mov_b32_e32 v126, v252
	v_mov_b32_e32 v127, v253
	v_add_co_u32_e32 v254, vcc, 0x1400, v254
	s_nop 1
	v_addc_co_u32_e32 v255, vcc, 0, v255, vcc
	global_load_dwordx4 v[236:239], v[254:255], off offset:32
	global_load_dwordx4 v[242:245], v[254:255], off offset:48
	global_load_dwordx4 v[246:249], v[254:255], off
	global_load_dwordx4 v[250:253], v[254:255], off offset:16
	v_xor_b32_e32 v92, 0x80000000, v84
	v_xor_b32_e32 v93, 0x80000000, v85
	v_xor_b32_e32 v94, 0x80000000, v86
	v_xor_b32_e32 v95, 0x80000000, v87
	v_xor_b32_e32 v96, 0x80000000, v88
	v_xor_b32_e32 v97, 0x80000000, v89
	v_xor_b32_e32 v98, 0x80000000, v90
	v_xor_b32_e32 v99, 0x80000000, v91
	v_cndmask_b32_e64 v87, v87, v95, s[40:41]
	v_cndmask_b32_e64 v86, v86, v94, s[40:41]
	v_cndmask_b32_e64 v85, v85, v93, s[40:41]
	v_cndmask_b32_e64 v84, v84, v92, s[40:41]
	v_cndmask_b32_e64 v91, v91, v99, s[40:41]
	v_cndmask_b32_e64 v90, v90, v98, s[40:41]
	v_cndmask_b32_e64 v89, v89, v97, s[40:41]
	v_cndmask_b32_e64 v88, v88, v96, s[40:41]
	v_pk_mul_f32 v[92:93], v[84:85], v[116:117]
	s_waitcnt lgkmcnt(3)
	v_pk_mul_f32 v[94:95], v[86:87], v[118:119]
	v_pk_mul_f32 v[110:111], v[88:89], v[112:113]
	s_waitcnt lgkmcnt(2)
	v_pk_mul_f32 v[112:113], v[90:91], v[114:115]
	v_pk_mul_f32 v[84:85], v[84:85], v[106:107]
	s_waitcnt lgkmcnt(1)
	v_pk_mul_f32 v[86:87], v[86:87], v[108:109]
	v_pk_mul_f32 v[102:103], v[88:89], v[102:103]
	s_waitcnt lgkmcnt(0)
	v_pk_mul_f32 v[104:105], v[90:91], v[104:105]
	v_pk_fma_f32 v[98:99], v[82:83], v[122:123], v[94:95]
	v_pk_fma_f32 v[96:97], v[80:81], v[120:121], v[92:93]
	v_pk_fma_f32 v[94:95], v[78:79], v[126:127], v[112:113]
	v_pk_fma_f32 v[92:93], v[76:77], v[124:125], v[110:111]
	v_pk_fma_f32 v[90:91], v[74:75], v[122:123], v[86:87]
	v_pk_fma_f32 v[88:89], v[72:73], v[120:121], v[84:85]
	v_pk_fma_f32 v[86:87], v[70:71], v[126:127], v[104:105]
	v_pk_fma_f32 v[84:85], v[68:69], v[124:125], v[102:103]

.LBB0_294:
	s_nop 1
	v_mov_b64_e32 v[68:69], s[22:23]
	v_mad_i64_i32 v[84:85], s[34:35], v190, s89, v[68:69]
	v_pk_mul_f32 v[66:67], v[66:67], v[192:193] op_sel_hi:[1,0]
	v_pk_mul_f32 v[64:65], v[64:65], v[192:193] op_sel_hi:[1,0]
	v_pk_mul_f32 v[62:63], v[62:63], v[192:193] op_sel_hi:[1,0]
	v_pk_mul_f32 v[60:61], v[60:61], v[192:193] op_sel_hi:[1,0]
	v_pk_mul_f32 v[58:59], v[58:59], v[192:193] op_sel_hi:[1,0]
	v_pk_mul_f32 v[56:57], v[56:57], v[192:193] op_sel_hi:[1,0]
	v_pk_mul_f32 v[54:55], v[54:55], v[192:193] op_sel_hi:[1,0]
	v_pk_mul_f32 v[52:53], v[52:53], v[192:193] op_sel_hi:[1,0]
	s_and_b64 vcc, exec, s[46:47]
	s_mov_b64 s[34:35], -1
	s_cbranch_vccnz .LBB0_304
	s_and_b64 vcc, exec, s[44:45]
	s_cbranch_vccnz .LBB0_300
	s_andn2_b64 vcc, exec, s[50:51]
	s_cbranch_vccnz .LBB0_301
	v_and_b32_e32 v69, 64, v221
	v_xor_b32_e32 v68, 16, v221
	v_add_u32_e32 v69, 64, v69
	v_cmp_lt_i32_e32 vcc, v68, v69
	v_mov_b64_e32 v[82:83], v[66:67]
	v_mov_b64_e32 v[74:75], v[58:59]
	v_cndmask_b32_e32 v68, v221, v68, vcc
	v_lshlrev_b32_e32 v68, 2, v68
	ds_bpermute_b32 v98, v68, v64
	ds_bpermute_b32 v94, v68, v60
	ds_bpermute_b32 v90, v68, v56
	ds_bpermute_b32 v86, v68, v52
	ds_bpermute_b32 v99, v68, v65
	ds_bpermute_b32 v95, v68, v61
	ds_bpermute_b32 v91, v68, v57
	ds_bpermute_b32 v87, v68, v53
	ds_bpermute_b32 v100, v68, v66
	ds_bpermute_b32 v96, v68, v62
	ds_bpermute_b32 v92, v68, v58
	ds_bpermute_b32 v88, v68, v54
	ds_bpermute_b32 v101, v68, v67
	ds_bpermute_b32 v97, v68, v63
	ds_bpermute_b32 v93, v68, v59
	ds_bpermute_b32 v89, v68, v55
	v_mov_b64_e32 v[70:71], v[54:55]
	v_mov_b64_e32 v[78:79], v[62:63]
	v_mov_b64_e32 v[80:81], v[64:65]
	v_mov_b64_e32 v[68:69], v[52:53]
	v_mov_b64_e32 v[72:73], v[56:57]
	v_mov_b64_e32 v[76:77], v[60:61]
	s_and_saveexec_b64 s[34:35], s[38:39]
	s_cbranch_execz .LBB0_299
	v_ashrrev_i32_e32 v191, 31, v190
	v_lshlrev_b64 v[68:69], 6, v[190:191]
	v_lshl_add_u64 v[76:77], s[26:27], 0, v[68:69]
	s_waitcnt lgkmcnt(0)
	s_waitcnt vmcnt(2)
	v_mov_b32_e32 v68, v236
	v_mov_b32_e32 v69, v237
	v_mov_b32_e32 v70, v238
	v_mov_b32_e32 v71, v239
	v_mov_b32_e32 v72, v242
	v_mov_b32_e32 v73, v243
	v_mov_b32_e32 v74, v244
	v_mov_b32_e32 v75, v245
	v_mov_b32_e32 v102, v246
	v_mov_b32_e32 v103, v247
	v_mov_b32_e32 v104, v248
	v_mov_b32_e32 v105, v249
	v_mov_b32_e32 v106, v250
	v_mov_b32_e32 v107, v251
	v_mov_b32_e32 v108, v252
	v_mov_b32_e32 v109, v253
	v_add_co_u32_e32 v254, vcc, 0x400, v254
	s_nop 1
	v_addc_co_u32_e32 v255, vcc, 0, v255, vcc
	global_load_dwordx4 v[236:239], v[254:255], off offset:32
	global_load_dwordx4 v[242:245], v[254:255], off offset:48
	global_load_dwordx4 v[246:249], v[254:255], off
	global_load_dwordx4 v[250:253], v[254:255], off offset:16
	v_xor_b32_e32 v76, 0x80000000, v68
	v_xor_b32_e32 v77, 0x80000000, v69
	v_xor_b32_e32 v78, 0x80000000, v70
	v_xor_b32_e32 v79, 0x80000000, v71
	v_xor_b32_e32 v80, 0x80000000, v72
	v_xor_b32_e32 v81, 0x80000000, v73
	v_xor_b32_e32 v82, 0x80000000, v74
	v_xor_b32_e32 v83, 0x80000000, v75
	v_cndmask_b32_e64 v71, v71, v79, s[40:41]
	v_cndmask_b32_e64 v70, v70, v78, s[40:41]
	v_cndmask_b32_e64 v69, v69, v77, s[40:41]
	v_cndmask_b32_e64 v68, v68, v76, s[40:41]
	v_cndmask_b32_e64 v75, v75, v83, s[40:41]
	v_cndmask_b32_e64 v74, v74, v82, s[40:41]
	v_cndmask_b32_e64 v73, v73, v81, s[40:41]
	v_cndmask_b32_e64 v72, v72, v80, s[40:41]
	v_pk_mul_f32 v[76:77], v[68:69], v[98:99]
	v_pk_mul_f32 v[78:79], v[70:71], v[100:101]
	v_pk_mul_f32 v[94:95], v[72:73], v[94:95]
	v_pk_mul_f32 v[96:97], v[74:75], v[96:97]
	v_pk_mul_f32 v[68:69], v[68:69], v[90:91]
	v_pk_mul_f32 v[70:71], v[70:71], v[92:93]
	v_pk_mul_f32 v[86:87], v[72:73], v[86:87]
	v_pk_mul_f32 v[88:89], v[74:75], v[88:89]
	v_pk_fma_f32 v[82:83], v[66:67], v[104:105], v[78:79]
	v_pk_fma_f32 v[80:81], v[64:65], v[102:103], v[76:77]
	v_pk_fma_f32 v[78:79], v[62:63], v[108:109], v[96:97]
	v_pk_fma_f32 v[76:77], v[60:61], v[106:107], v[94:95]
	v_pk_fma_f32 v[74:75], v[58:59], v[104:105], v[70:71]
	v_pk_fma_f32 v[72:73], v[56:57], v[102:103], v[68:69]
	v_pk_fma_f32 v[70:71], v[54:55], v[108:109], v[88:89]
	v_pk_fma_f32 v[68:69], v[52:53], v[106:107], v[86:87]

.LBB0_306:
	s_nop 1
	v_mov_b64_e32 v[52:53], s[22:23]
	v_mad_i64_i32 v[68:69], s[34:35], v186, s89, v[52:53]
	v_pk_mul_f32 v[50:51], v[50:51], v[188:189] op_sel_hi:[1,0]
	v_pk_mul_f32 v[48:49], v[48:49], v[188:189] op_sel_hi:[1,0]
	v_pk_mul_f32 v[46:47], v[46:47], v[188:189] op_sel_hi:[1,0]
	v_pk_mul_f32 v[44:45], v[44:45], v[188:189] op_sel_hi:[1,0]
	v_pk_mul_f32 v[42:43], v[42:43], v[188:189] op_sel_hi:[1,0]
	v_pk_mul_f32 v[40:41], v[40:41], v[188:189] op_sel_hi:[1,0]
	v_pk_mul_f32 v[38:39], v[38:39], v[188:189] op_sel_hi:[1,0]
	v_pk_mul_f32 v[36:37], v[36:37], v[188:189] op_sel_hi:[1,0]
	s_and_b64 vcc, exec, s[46:47]
	s_mov_b64 s[34:35], -1
	s_cbranch_vccnz .LBB0_316
	s_and_b64 vcc, exec, s[44:45]
	s_cbranch_vccnz .LBB0_312
	s_andn2_b64 vcc, exec, s[50:51]
	s_cbranch_vccnz .LBB0_313
	v_and_b32_e32 v53, 64, v221
	v_xor_b32_e32 v52, 16, v221
	v_add_u32_e32 v53, 64, v53
	v_cmp_lt_i32_e32 vcc, v52, v53
	v_mov_b64_e32 v[66:67], v[50:51]
	v_mov_b64_e32 v[58:59], v[42:43]
	v_cndmask_b32_e32 v52, v221, v52, vcc
	v_lshlrev_b32_e32 v52, 2, v52
	ds_bpermute_b32 v82, v52, v48
	ds_bpermute_b32 v78, v52, v44
	ds_bpermute_b32 v74, v52, v40
	ds_bpermute_b32 v70, v52, v36
	ds_bpermute_b32 v83, v52, v49
	ds_bpermute_b32 v79, v52, v45
	ds_bpermute_b32 v75, v52, v41
	ds_bpermute_b32 v71, v52, v37
	ds_bpermute_b32 v84, v52, v50
	ds_bpermute_b32 v80, v52, v46
	ds_bpermute_b32 v76, v52, v42
	ds_bpermute_b32 v72, v52, v38
	ds_bpermute_b32 v85, v52, v51
	ds_bpermute_b32 v81, v52, v47
	ds_bpermute_b32 v77, v52, v43
	ds_bpermute_b32 v73, v52, v39
	v_mov_b64_e32 v[54:55], v[38:39]
	v_mov_b64_e32 v[62:63], v[46:47]
	v_mov_b64_e32 v[64:65], v[48:49]
	v_mov_b64_e32 v[52:53], v[36:37]
	v_mov_b64_e32 v[56:57], v[40:41]
	v_mov_b64_e32 v[60:61], v[44:45]
	s_and_saveexec_b64 s[34:35], s[38:39]
	s_cbranch_execz .LBB0_311
	v_ashrrev_i32_e32 v187, 31, v186
	v_lshlrev_b64 v[52:53], 6, v[186:187]
	v_lshl_add_u64 v[60:61], s[26:27], 0, v[52:53]
	s_waitcnt lgkmcnt(0)
	s_waitcnt vmcnt(2)
	v_mov_b32_e32 v52, v236
	v_mov_b32_e32 v53, v237
	v_mov_b32_e32 v54, v238
	v_mov_b32_e32 v55, v239
	v_mov_b32_e32 v56, v242
	v_mov_b32_e32 v57, v243
	v_mov_b32_e32 v58, v244
	v_mov_b32_e32 v59, v245
	v_mov_b32_e32 v86, v246
	v_mov_b32_e32 v87, v247
	v_mov_b32_e32 v88, v248
	v_mov_b32_e32 v89, v249
	v_mov_b32_e32 v90, v250
	v_mov_b32_e32 v91, v251
	v_mov_b32_e32 v92, v252
	v_mov_b32_e32 v93, v253
	v_add_co_u32_e32 v254, vcc, 0x400, v254
	s_nop 1
	v_addc_co_u32_e32 v255, vcc, 0, v255, vcc
	global_load_dwordx4 v[236:239], v[254:255], off offset:32
	global_load_dwordx4 v[242:245], v[254:255], off offset:48
	global_load_dwordx4 v[246:249], v[254:255], off
	global_load_dwordx4 v[250:253], v[254:255], off offset:16
	v_xor_b32_e32 v60, 0x80000000, v52
	v_xor_b32_e32 v61, 0x80000000, v53
	v_xor_b32_e32 v62, 0x80000000, v54
	v_xor_b32_e32 v63, 0x80000000, v55
	v_xor_b32_e32 v64, 0x80000000, v56
	v_xor_b32_e32 v65, 0x80000000, v57
	v_xor_b32_e32 v66, 0x80000000, v58
	v_xor_b32_e32 v67, 0x80000000, v59
	v_cndmask_b32_e64 v55, v55, v63, s[40:41]
	v_cndmask_b32_e64 v54, v54, v62, s[40:41]
	v_cndmask_b32_e64 v53, v53, v61, s[40:41]
	v_cndmask_b32_e64 v52, v52, v60, s[40:41]
	v_cndmask_b32_e64 v59, v59, v67, s[40:41]
	v_cndmask_b32_e64 v58, v58, v66, s[40:41]
	v_cndmask_b32_e64 v57, v57, v65, s[40:41]
	v_cndmask_b32_e64 v56, v56, v64, s[40:41]
	v_pk_mul_f32 v[60:61], v[52:53], v[82:83]
	v_pk_mul_f32 v[62:63], v[54:55], v[84:85]
	v_pk_mul_f32 v[78:79], v[56:57], v[78:79]
	v_pk_mul_f32 v[80:81], v[58:59], v[80:81]
	v_pk_mul_f32 v[52:53], v[52:53], v[74:75]
	v_pk_mul_f32 v[54:55], v[54:55], v[76:77]
	v_pk_mul_f32 v[70:71], v[56:57], v[70:71]
	v_pk_mul_f32 v[72:73], v[58:59], v[72:73]
	v_pk_fma_f32 v[66:67], v[50:51], v[88:89], v[62:63]
	v_pk_fma_f32 v[64:65], v[48:49], v[86:87], v[60:61]
	v_pk_fma_f32 v[62:63], v[46:47], v[92:93], v[80:81]
	v_pk_fma_f32 v[60:61], v[44:45], v[90:91], v[78:79]
	v_pk_fma_f32 v[58:59], v[42:43], v[88:89], v[54:55]
	v_pk_fma_f32 v[56:57], v[40:41], v[86:87], v[52:53]
	v_pk_fma_f32 v[54:55], v[38:39], v[92:93], v[72:73]
	v_pk_fma_f32 v[52:53], v[36:37], v[90:91], v[70:71]

.LBB0_318:
	s_nop 1
	v_mov_b64_e32 v[36:37], s[22:23]
	v_mad_i64_i32 v[52:53], s[34:35], v182, s89, v[36:37]
	v_pk_mul_f32 v[34:35], v[34:35], v[184:185] op_sel_hi:[1,0]
	v_pk_mul_f32 v[32:33], v[32:33], v[184:185] op_sel_hi:[1,0]
	v_pk_mul_f32 v[30:31], v[30:31], v[184:185] op_sel_hi:[1,0]
	v_pk_mul_f32 v[28:29], v[28:29], v[184:185] op_sel_hi:[1,0]
	v_pk_mul_f32 v[26:27], v[26:27], v[184:185] op_sel_hi:[1,0]
	v_pk_mul_f32 v[24:25], v[24:25], v[184:185] op_sel_hi:[1,0]
	v_pk_mul_f32 v[22:23], v[22:23], v[184:185] op_sel_hi:[1,0]
	v_pk_mul_f32 v[20:21], v[20:21], v[184:185] op_sel_hi:[1,0]
	s_and_b64 vcc, exec, s[46:47]
	s_mov_b64 s[34:35], -1
	s_cbranch_vccnz .LBB0_328
	s_and_b64 vcc, exec, s[44:45]
	s_cbranch_vccnz .LBB0_324
	s_andn2_b64 vcc, exec, s[50:51]
	s_cbranch_vccnz .LBB0_325
	v_and_b32_e32 v37, 64, v221
	v_xor_b32_e32 v36, 16, v221
	v_add_u32_e32 v37, 64, v37
	v_cmp_lt_i32_e32 vcc, v36, v37
	v_mov_b64_e32 v[50:51], v[34:35]
	v_mov_b64_e32 v[42:43], v[26:27]
	v_cndmask_b32_e32 v36, v221, v36, vcc
	v_lshlrev_b32_e32 v36, 2, v36
	ds_bpermute_b32 v66, v36, v32
	ds_bpermute_b32 v62, v36, v28
	ds_bpermute_b32 v58, v36, v24
	ds_bpermute_b32 v54, v36, v20
	ds_bpermute_b32 v67, v36, v33
	ds_bpermute_b32 v63, v36, v29
	ds_bpermute_b32 v59, v36, v25
	ds_bpermute_b32 v55, v36, v21
	ds_bpermute_b32 v68, v36, v34
	ds_bpermute_b32 v64, v36, v30
	ds_bpermute_b32 v60, v36, v26
	ds_bpermute_b32 v56, v36, v22
	ds_bpermute_b32 v69, v36, v35
	ds_bpermute_b32 v65, v36, v31
	ds_bpermute_b32 v61, v36, v27
	ds_bpermute_b32 v57, v36, v23
	v_mov_b64_e32 v[38:39], v[22:23]
	v_mov_b64_e32 v[46:47], v[30:31]
	v_mov_b64_e32 v[48:49], v[32:33]
	v_mov_b64_e32 v[36:37], v[20:21]
	v_mov_b64_e32 v[40:41], v[24:25]
	v_mov_b64_e32 v[44:45], v[28:29]
	s_and_saveexec_b64 s[34:35], s[38:39]
	s_cbranch_execz .LBB0_323
	v_ashrrev_i32_e32 v183, 31, v182
	v_lshlrev_b64 v[36:37], 6, v[182:183]
	v_lshl_add_u64 v[44:45], s[26:27], 0, v[36:37]
	s_waitcnt lgkmcnt(0)
	s_waitcnt vmcnt(2)
	v_mov_b32_e32 v36, v236
	v_mov_b32_e32 v37, v237
	v_mov_b32_e32 v38, v238
	v_mov_b32_e32 v39, v239
	v_mov_b32_e32 v40, v242
	v_mov_b32_e32 v41, v243
	v_mov_b32_e32 v42, v244
	v_mov_b32_e32 v43, v245
	v_mov_b32_e32 v70, v246
	v_mov_b32_e32 v71, v247
	v_mov_b32_e32 v72, v248
	v_mov_b32_e32 v73, v249
	v_mov_b32_e32 v74, v250
	v_mov_b32_e32 v75, v251
	v_mov_b32_e32 v76, v252
	v_mov_b32_e32 v77, v253
	v_add_co_u32_e32 v254, vcc, 0x400, v254
	s_nop 1
	v_addc_co_u32_e32 v255, vcc, 0, v255, vcc
	global_load_dwordx4 v[236:239], v[254:255], off offset:32
	global_load_dwordx4 v[242:245], v[254:255], off offset:48
	global_load_dwordx4 v[246:249], v[254:255], off
	global_load_dwordx4 v[250:253], v[254:255], off offset:16
	v_xor_b32_e32 v44, 0x80000000, v36
	v_xor_b32_e32 v45, 0x80000000, v37
	v_xor_b32_e32 v46, 0x80000000, v38
	v_xor_b32_e32 v47, 0x80000000, v39
	v_xor_b32_e32 v48, 0x80000000, v40
	v_xor_b32_e32 v49, 0x80000000, v41
	v_xor_b32_e32 v50, 0x80000000, v42
	v_xor_b32_e32 v51, 0x80000000, v43
	v_cndmask_b32_e64 v39, v39, v47, s[40:41]
	v_cndmask_b32_e64 v38, v38, v46, s[40:41]
	v_cndmask_b32_e64 v37, v37, v45, s[40:41]
	v_cndmask_b32_e64 v36, v36, v44, s[40:41]
	v_cndmask_b32_e64 v43, v43, v51, s[40:41]
	v_cndmask_b32_e64 v42, v42, v50, s[40:41]
	v_cndmask_b32_e64 v41, v41, v49, s[40:41]
	v_cndmask_b32_e64 v40, v40, v48, s[40:41]
	v_pk_mul_f32 v[44:45], v[36:37], v[66:67]
	v_pk_mul_f32 v[46:47], v[38:39], v[68:69]
	v_pk_mul_f32 v[62:63], v[40:41], v[62:63]
	v_pk_mul_f32 v[64:65], v[42:43], v[64:65]
	v_pk_mul_f32 v[36:37], v[36:37], v[58:59]
	v_pk_mul_f32 v[38:39], v[38:39], v[60:61]
	v_pk_mul_f32 v[54:55], v[40:41], v[54:55]
	v_pk_mul_f32 v[56:57], v[42:43], v[56:57]
	v_pk_fma_f32 v[50:51], v[34:35], v[72:73], v[46:47]
	v_pk_fma_f32 v[48:49], v[32:33], v[70:71], v[44:45]
	v_pk_fma_f32 v[46:47], v[30:31], v[76:77], v[64:65]
	v_pk_fma_f32 v[44:45], v[28:29], v[74:75], v[62:63]
	v_pk_fma_f32 v[42:43], v[26:27], v[72:73], v[38:39]
	v_pk_fma_f32 v[40:41], v[24:25], v[70:71], v[36:37]
	v_pk_fma_f32 v[38:39], v[22:23], v[76:77], v[56:57]
	v_pk_fma_f32 v[36:37], v[20:21], v[74:75], v[54:55]

.LBB0_330:
	s_nop 1
	v_mov_b64_e32 v[20:21], s[22:23]
	v_mad_i64_i32 v[36:37], s[34:35], v178, s89, v[20:21]
	v_pk_mul_f32 v[18:19], v[18:19], v[180:181] op_sel_hi:[1,0]
	v_pk_mul_f32 v[16:17], v[16:17], v[180:181] op_sel_hi:[1,0]
	v_pk_mul_f32 v[14:15], v[14:15], v[180:181] op_sel_hi:[1,0]
	v_pk_mul_f32 v[12:13], v[12:13], v[180:181] op_sel_hi:[1,0]
	v_pk_mul_f32 v[10:11], v[10:11], v[180:181] op_sel_hi:[1,0]
	v_pk_mul_f32 v[8:9], v[8:9], v[180:181] op_sel_hi:[1,0]
	v_pk_mul_f32 v[6:7], v[6:7], v[180:181] op_sel_hi:[1,0]
	v_pk_mul_f32 v[4:5], v[4:5], v[180:181] op_sel_hi:[1,0]
	s_and_b64 vcc, exec, s[46:47]
	s_mov_b64 s[34:35], -1
	s_cbranch_vccnz .LBB0_340
	s_and_b64 vcc, exec, s[44:45]
	s_cbranch_vccnz .LBB0_336
	s_andn2_b64 vcc, exec, s[50:51]
	s_cbranch_vccnz .LBB0_337
	v_and_b32_e32 v21, 64, v221
	v_xor_b32_e32 v20, 16, v221
	v_add_u32_e32 v21, 64, v21
	v_cmp_lt_i32_e32 vcc, v20, v21
	v_mov_b64_e32 v[34:35], v[18:19]
	v_mov_b64_e32 v[26:27], v[10:11]
	v_cndmask_b32_e32 v20, v221, v20, vcc
	v_lshlrev_b32_e32 v20, 2, v20
	ds_bpermute_b32 v50, v20, v16
	ds_bpermute_b32 v46, v20, v12
	ds_bpermute_b32 v42, v20, v8
	ds_bpermute_b32 v38, v20, v4
	ds_bpermute_b32 v51, v20, v17
	ds_bpermute_b32 v47, v20, v13
	ds_bpermute_b32 v43, v20, v9
	ds_bpermute_b32 v39, v20, v5
	ds_bpermute_b32 v52, v20, v18
	ds_bpermute_b32 v48, v20, v14
	ds_bpermute_b32 v44, v20, v10
	ds_bpermute_b32 v40, v20, v6
	ds_bpermute_b32 v53, v20, v19
	ds_bpermute_b32 v49, v20, v15
	ds_bpermute_b32 v45, v20, v11
	ds_bpermute_b32 v41, v20, v7
	v_mov_b64_e32 v[22:23], v[6:7]
	v_mov_b64_e32 v[30:31], v[14:15]
	v_mov_b64_e32 v[32:33], v[16:17]
	v_mov_b64_e32 v[20:21], v[4:5]
	v_mov_b64_e32 v[24:25], v[8:9]
	v_mov_b64_e32 v[28:29], v[12:13]
	s_and_saveexec_b64 s[34:35], s[38:39]
	s_cbranch_execz .LBB0_335
	v_ashrrev_i32_e32 v179, 31, v178
	v_lshlrev_b64 v[20:21], 6, v[178:179]
	v_lshl_add_u64 v[28:29], s[26:27], 0, v[20:21]
	s_waitcnt lgkmcnt(0)
	s_waitcnt vmcnt(2)
	v_mov_b32_e32 v20, v236
	v_mov_b32_e32 v21, v237
	v_mov_b32_e32 v22, v238
	v_mov_b32_e32 v23, v239
	v_mov_b32_e32 v24, v242
	v_mov_b32_e32 v25, v243
	v_mov_b32_e32 v26, v244
	v_mov_b32_e32 v27, v245
	v_mov_b32_e32 v54, v246
	v_mov_b32_e32 v55, v247
	v_mov_b32_e32 v56, v248
	v_mov_b32_e32 v57, v249
	v_mov_b32_e32 v58, v250
	v_mov_b32_e32 v59, v251
	v_mov_b32_e32 v60, v252
	v_mov_b32_e32 v61, v253
	v_xor_b32_e32 v28, 0x80000000, v20
	v_xor_b32_e32 v29, 0x80000000, v21
	v_xor_b32_e32 v30, 0x80000000, v22
	v_xor_b32_e32 v31, 0x80000000, v23
	v_xor_b32_e32 v32, 0x80000000, v24
	v_xor_b32_e32 v33, 0x80000000, v25
	v_xor_b32_e32 v34, 0x80000000, v26
	v_xor_b32_e32 v35, 0x80000000, v27
	v_cndmask_b32_e64 v23, v23, v31, s[40:41]
	v_cndmask_b32_e64 v22, v22, v30, s[40:41]
	v_cndmask_b32_e64 v21, v21, v29, s[40:41]
	v_cndmask_b32_e64 v20, v20, v28, s[40:41]
	v_cndmask_b32_e64 v27, v27, v35, s[40:41]
	v_cndmask_b32_e64 v26, v26, v34, s[40:41]
	v_cndmask_b32_e64 v25, v25, v33, s[40:41]
	v_cndmask_b32_e64 v24, v24, v32, s[40:41]
	v_pk_mul_f32 v[28:29], v[20:21], v[50:51]
	v_pk_mul_f32 v[30:31], v[22:23], v[52:53]
	v_pk_mul_f32 v[46:47], v[24:25], v[46:47]
	v_pk_mul_f32 v[48:49], v[26:27], v[48:49]
	v_pk_mul_f32 v[20:21], v[20:21], v[42:43]
	v_pk_mul_f32 v[22:23], v[22:23], v[44:45]
	v_pk_mul_f32 v[38:39], v[24:25], v[38:39]
	v_pk_mul_f32 v[40:41], v[26:27], v[40:41]
	v_pk_fma_f32 v[34:35], v[18:19], v[56:57], v[30:31]
	v_pk_fma_f32 v[32:33], v[16:17], v[54:55], v[28:29]
	v_pk_fma_f32 v[30:31], v[14:15], v[60:61], v[48:49]
	v_pk_fma_f32 v[28:29], v[12:13], v[58:59], v[46:47]
	v_pk_fma_f32 v[26:27], v[10:11], v[56:57], v[22:23]
	v_pk_fma_f32 v[24:25], v[8:9], v[54:55], v[20:21]
	v_pk_fma_f32 v[22:23], v[6:7], v[60:61], v[40:41]
	v_pk_fma_f32 v[20:21], v[4:5], v[58:59], v[38:39]
